# stack: LDS-DMA a_lr tail + g3 invariant-load hoist and wait trimming + g1 MFMA-section read hoist on top of the previous best
# speedup vs baseline: 1.0024x; 1.0024x over previous
; #define LAS __attribute__((address_space(3)))
; __device__ __forceinline__ unsigned pk2(float lo, float hi) { return pg8::cvt_pk_bf16_safe(lo, hi); }
; __device__ __forceinline__ void phase_g1(const Args& a, LAS unsigned char* lds, int tid, int lane, int wave) {
;     ...
;         bf16x8 vf[2][2]; vt_frags(Vs, wave, lane, vf);
;         __syncthreads();
;         f32x4 acc[8][2];
; #pragma unroll
;         for (int mt = 0; mt < 8; ++mt)
; #pragma unroll
;             for (int nt = 0; nt < 2; ++nt) acc[mt][nt] = (f32x4){0.f, 0.f, 0.f, 0.f};
; #pragma unroll
;         for (int mt = 0; mt < 8; ++mt)
; #pragma unroll
;             for (int ks = 0; ks < 2; ++ks) { const bf16x8 af = *(const LAS bf16x8*)(kdT + (16 * mt + r16) * 72 + 32 * ks + 8 * q4);
; #pragma unroll
;                 for (int nt = 0; nt < 2; ++nt) acc[mt][nt] = __builtin_amdgcn_mfma_f32_16x16x32_bf16(af, vf[nt][ks], acc[mt][nt], 0, 0, 0); }
;         bf16* Su = S + (size_t)unit * 32768;
; #pragma unroll
;         for (int mt = 0; mt < 8; ++mt)
; #pragma unroll
;             for (int nt = 0; nt < 2; ++nt) { v2u w; w.x = pk2(acc[mt][nt][0], acc[mt][nt][1]); w.y = pk2(acc[mt][nt][2], acc[mt][nt][3]);
;                 *(v2u*)(Su + (32 * wave + 16 * nt + r16) * 128 + 16 * mt + 4 * q4) = w; }
.LBB0_283:
	s_or_b64 exec, exec, s[28:29]
	ds_read_b64_tr_b16 v[96:97], v58
	ds_read_b64_tr_b16 v[98:99], v58 offset:2112
	ds_read_b64_tr_b16 v[92:93], v58 offset:16896
	ds_read_b64_tr_b16 v[94:95], v58 offset:19008
	ds_read_b64_tr_b16 v[88:89], v58 offset:32
	ds_read_b64_tr_b16 v[90:91], v58 offset:2144
	ds_read_b64_tr_b16 v[44:45], v58 offset:16928
	ds_read_b64_tr_b16 v[46:47], v58 offset:19040
	s_waitcnt lgkmcnt(0)
	s_waitcnt lgkmcnt(0)
	s_barrier
	ds_read_b128 v[100:103], v78 offset:8192
	ds_read_b128 v[104:107], v78 offset:8256
	ds_read_b128 v[176:179], v78 offset:10496
	ds_read_b128 v[180:183], v78 offset:10560
	ds_read_b128 v[184:187], v78 offset:12800
	ds_read_b128 v[188:191], v78 offset:12864
	s_waitcnt lgkmcnt(5)
	v_mfma_f32_16x16x32_bf16 v[108:111], v[100:103], v[96:99], 0
	s_ashr_i32 s27, s26, 31
	s_lshl_b64 s[26:27], s[26:27], 16
	v_lshl_add_u64 v[168:169], v[30:31], 0, s[26:27]
	v_mfma_f32_16x16x32_bf16 v[100:103], v[100:103], v[88:91], 0
	v_lshl_add_u64 v[170:171], v[32:33], 1, v[168:169]
	v_add_u32_e32 v38, s48, v38
	s_add_i32 s49, s49, s50
	s_waitcnt lgkmcnt(4)
	v_mfma_f32_16x16x32_bf16 v[108:111], v[104:107], v[92:95], v[108:111]
	s_add_i32 s51, s51, s52
	s_and_b64 vcc, exec, s[14:15]
	s_mov_b32 s26, s73
	v_mfma_f32_16x16x32_bf16 v[100:103], v[104:107], v[44:47], v[100:103]
	s_waitcnt lgkmcnt(3)
	v_mfma_f32_16x16x32_bf16 v[116:119], v[176:179], v[96:99], 0
	s_nop 3
	v_cvt_pk_bf16_f32 v100, v100, v101
	v_cvt_pk_bf16_f32 v101, v102, v103
	v_mfma_f32_16x16x32_bf16 v[104:107], v[176:179], v[88:91], 0
	s_waitcnt lgkmcnt(2)
	v_mfma_f32_16x16x32_bf16 v[116:119], v[180:183], v[92:95], v[116:119]
	v_mfma_f32_16x16x32_bf16 v[104:107], v[180:183], v[44:47], v[104:107]
	s_waitcnt lgkmcnt(1)
	v_mfma_f32_16x16x32_bf16 v[124:127], v[184:187], v[96:99], 0
	s_nop 3
	v_cvt_pk_bf16_f32 v104, v104, v105
	v_cvt_pk_bf16_f32 v105, v106, v107
	v_mfma_f32_16x16x32_bf16 v[112:115], v[184:187], v[88:91], 0
	s_waitcnt lgkmcnt(0)
	v_mfma_f32_16x16x32_bf16 v[124:127], v[188:191], v[92:95], v[124:127]
	v_mfma_f32_16x16x32_bf16 v[112:115], v[188:191], v[44:47], v[112:115]
	ds_read_b128 v[120:123], v79 offset:8192
	ds_read_b128 v[128:131], v79 offset:8256
	ds_read_b128 v[136:139], v78 offset:17408
	ds_read_b128 v[140:143], v78 offset:17472
	ds_read_b128 v[144:147], v78 offset:19712
	ds_read_b128 v[148:151], v78 offset:19776
	ds_read_b128 v[152:155], v78 offset:22016
	ds_read_b128 v[156:159], v78 offset:22080
	s_waitcnt lgkmcnt(7)
	v_mfma_f32_16x16x32_bf16 v[132:135], v[120:123], v[96:99], 0
	ds_read_b128 v[160:163], v80 offset:8192
	ds_read_b128 v[164:167], v80 offset:8256
	v_cvt_pk_bf16_f32 v112, v112, v113
	v_cvt_pk_bf16_f32 v113, v114, v115
	v_mfma_f32_16x16x32_bf16 v[120:123], v[120:123], v[88:91], 0
	s_waitcnt lgkmcnt(8)
	v_mfma_f32_16x16x32_bf16 v[132:135], v[128:131], v[92:95], v[132:135]
	v_mfma_f32_16x16x32_bf16 v[120:123], v[128:131], v[44:47], v[120:123]
	v_cvt_pk_bf16_f32 v128, v108, v109
	v_cvt_pk_bf16_f32 v129, v110, v111
	global_store_dwordx2 v[170:171], v[128:129], off
	s_waitcnt lgkmcnt(7)
	v_mfma_f32_16x16x32_bf16 v[108:111], v[136:139], v[96:99], 0
	v_mfma_f32_16x16x32_bf16 v[128:131], v[136:139], v[88:91], 0
	v_lshl_add_u64 v[136:137], v[34:35], 1, v[168:169]
	global_store_dwordx2 v[136:137], v[100:101], off
	global_store_dwordx2 v[136:137], v[104:105], off offset:32
	s_waitcnt lgkmcnt(6)
	v_mfma_f32_16x16x32_bf16 v[100:103], v[140:143], v[92:95], v[108:111]
	global_store_dwordx2 v[136:137], v[112:113], off offset:64
	v_cvt_pk_bf16_f32 v112, v132, v133
	v_cvt_pk_bf16_f32 v113, v134, v135
	v_cvt_pk_bf16_f32 v108, v116, v117
	v_cvt_pk_bf16_f32 v116, v124, v125
	v_cvt_pk_bf16_f32 v117, v126, v127
	v_cvt_pk_bf16_f32 v109, v118, v119
	global_store_dwordx2 v[170:171], v[116:117], off offset:64
	s_waitcnt lgkmcnt(5)
	v_mfma_f32_16x16x32_bf16 v[116:119], v[144:147], v[88:91], 0
	global_store_dwordx2 v[170:171], v[108:109], off offset:32
	global_store_dwordx2 v[170:171], v[112:113], off offset:96
	v_cvt_pk_bf16_f32 v100, v100, v101
	v_mfma_f32_16x16x32_bf16 v[104:107], v[144:147], v[96:99], 0
	v_cvt_pk_bf16_f32 v101, v102, v103
	global_store_dwordx2 v[170:171], v[100:101], off offset:128
	v_mfma_f32_16x16x32_bf16 v[108:111], v[140:143], v[44:47], v[128:131]
	s_waitcnt lgkmcnt(4)
	v_mfma_f32_16x16x32_bf16 v[112:115], v[148:151], v[44:47], v[116:119]
	s_nop 2
	v_cvt_pk_bf16_f32 v116, v120, v121
	v_cvt_pk_bf16_f32 v117, v122, v123
	global_store_dwordx2 v[136:137], v[116:117], off offset:96
	s_waitcnt lgkmcnt(3)
	v_mfma_f32_16x16x32_bf16 v[116:119], v[152:155], v[96:99], 0
	v_cvt_pk_bf16_f32 v108, v108, v109
	v_cvt_pk_bf16_f32 v109, v110, v111
	global_store_dwordx2 v[136:137], v[108:109], off offset:128
	v_mfma_f32_16x16x32_bf16 v[100:103], v[152:155], v[88:91], 0
	s_waitcnt lgkmcnt(1)
	v_mfma_f32_16x16x32_bf16 v[96:99], v[160:163], v[96:99], 0
	v_mfma_f32_16x16x32_bf16 v[88:91], v[160:163], v[88:91], 0
	v_mfma_f32_16x16x32_bf16 v[104:107], v[148:151], v[92:95], v[104:107]
	v_mfma_f32_16x16x32_bf16 v[108:111], v[156:159], v[92:95], v[116:119]
	v_mfma_f32_16x16x32_bf16 v[100:103], v[156:159], v[44:47], v[100:103]
	s_nop 5
	v_cvt_pk_bf16_f32 v104, v104, v105
	v_cvt_pk_bf16_f32 v105, v106, v107
	global_store_dwordx2 v[170:171], v[104:105], off offset:160
	s_waitcnt lgkmcnt(0)
	v_mfma_f32_16x16x32_bf16 v[92:95], v[164:167], v[92:95], v[96:99]
	v_cvt_pk_bf16_f32 v104, v112, v113
	v_cvt_pk_bf16_f32 v105, v114, v115
	global_store_dwordx2 v[136:137], v[104:105], off offset:160
	v_mfma_f32_16x16x32_bf16 v[44:47], v[164:167], v[44:47], v[88:91]
	v_cvt_pk_bf16_f32 v104, v108, v109
	v_cvt_pk_bf16_f32 v105, v110, v111
	v_cvt_pk_bf16_f32 v100, v100, v101
	v_cvt_pk_bf16_f32 v101, v102, v103
	v_cvt_pk_bf16_f32 v92, v92, v93
	v_cvt_pk_bf16_f32 v93, v94, v95
	s_nop 1
	v_cvt_pk_bf16_f32 v44, v44, v45
	v_cvt_pk_bf16_f32 v45, v46, v47
	global_store_dwordx2 v[170:171], v[104:105], off offset:192
	global_store_dwordx2 v[136:137], v[100:101], off offset:192
	global_store_dwordx2 v[170:171], v[92:93], off offset:224
	global_store_dwordx2 v[136:137], v[44:45], off offset:224
	s_barrier
	s_cbranch_vccnz .LBB0_292
